# sample_ssd head loop: A_log, D and z-gate loads software-pipelined one head ahead, top-of-iteration and mid-loop waits removed
# speedup vs baseline: 1.0152x; 1.0016x over previous
; __device__ __forceinline__ void sample_ssd(const Params& p, unsigned char* smem, int job) {
;     ...
;     const int pp = tid >> 3, nq = tid & 7;
;     f32x4 snext[4];
; #pragma unroll
;     for (int i = 0; i < 4; ++i) snext[i] = __builtin_nontemporal_load((const f32x4*)(p.in[3] + ((size_t)(b * 32 + g * 16) * 64 + pp) * 128 + nq * 4 + 32 * i));
;     for (int hh = 0; hh < 16; ++hh) {
;         const int h = g * 16 + hh;
;         const float A_h = -__expf(p.in[14][h]), D_h = p.in[15][h];
.LBB0_676:
	s_or_b64 exec, exec, s[0:1]
	v_cndmask_b32_e64 v12, 0, 1, s[80:81]
	v_readlane_b32 s56, v254, 59
	v_readfirstlane_b32 s0, v12
	s_lshl_b32 s40, s0, 4
	s_lshl_b32 s0, s0, 6
	v_readlane_b32 s70, v255, 9
	v_readlane_b32 s71, v255, 10
	s_add_u32 s86, s70, s0
	v_readlane_b32 s68, v255, 7
	s_addc_u32 s87, s71, 0
	v_readlane_b32 s69, v255, 8
	s_add_u32 s88, s68, s0
	s_addc_u32 s89, s69, 0
	s_lshl_b32 s43, s26, 5
	s_lshl_b32 s44, s27, 4
	v_readlane_b32 s57, v254, 60
	v_readlane_b32 s58, v254, 61
	v_readlane_b32 s59, v254, 62
	v_readlane_b32 s60, v254, 63
	v_readlane_b32 s61, v255, 0
	v_readlane_b32 s62, v255, 1
	v_readlane_b32 s63, v255, 2
	v_readlane_b32 s64, v255, 3
	v_readlane_b32 s65, v255, 4
	v_readlane_b32 s66, v255, 5
	v_readlane_b32 s67, v255, 6
	s_or_b32 s0, s43, s44
	s_ashr_i32 s1, s0, 31
	v_readlane_b32 s56, v254, 43
	s_lshl_b64 s[0:1], s[0:1], 15
	v_readlane_b32 s62, v254, 49
	v_ashrrev_i32_e32 v45, 31, v44
	v_readlane_b32 s63, v254, 50
	s_add_u32 s0, s62, s0
	s_addc_u32 s1, s63, s1
	v_lshlrev_b64 v[8:9], 9, v[44:45]
	v_lshlrev_b32_e32 v6, 4, v4
	v_lshl_add_u64 v[10:11], s[0:1], 0, v[8:9]
	s_waitcnt lgkmcnt(0)
	v_mov_b32_e32 v7, v149
	v_lshl_add_u64 v[10:11], v[10:11], 0, v[6:7]
	s_barrier
	global_load_dwordx4 v[32:35], v[10:11], off nt
	global_load_dwordx4 v[28:31], v[10:11], off offset:128 nt
	global_load_dwordx4 v[24:27], v[10:11], off offset:256 nt
	global_load_dwordx4 v[20:23], v[10:11], off offset:384 nt
	v_xor_b32_e32 v10, 8, v206
	v_cmp_lt_i32_e64 s[0:1], v10, v5
	v_add_u32_e32 v83, 0, v6
	v_and_b32_e32 v7, 63, v49
	v_cndmask_b32_e64 v10, v206, v10, s[0:1]
	v_lshlrev_b32_e32 v77, 2, v10
	v_xor_b32_e32 v10, 16, v206
	v_cmp_lt_i32_e64 s[0:1], v10, v5
	v_add_u32_e32 v79, v83, v6
	v_lshlrev_b32_e32 v148, 11, v12
	v_cndmask_b32_e64 v10, v206, v10, s[0:1]
	v_lshlrev_b32_e32 v78, 2, v10
	v_xor_b32_e32 v10, 32, v206
	v_cmp_lt_i32_e64 s[0:1], v10, v5
	v_lshlrev_b32_e32 v75, 2, v7
	s_mov_b32 s36, 0xa300
	v_cndmask_b32_e64 v5, v206, v10, s[0:1]
	v_lshlrev_b32_e32 v76, 2, v5
	v_sub_u32_e32 v5, 0, v6
	v_lshlrev_b32_e32 v6, 2, v44
	v_and_b32_e32 v10, 0xffffffe0, v6
	v_add_u32_e32 v85, 0x2000, v6
	v_add_u32_e32 v6, s33, v4
	v_cmp_gt_u32_e64 s[0:1], 8, v7
	v_add3_u32 v84, v10, v75, s36
	v_ashrrev_i32_e32 v7, 31, v6
	v_mad_i64_i32 v[10:11], s[36:37], v6, s45, v[148:149]
	v_lshlrev_b64 v[6:7], 13, v[6:7]
	s_or_b32 s36, s43, s40
	v_lshlrev_b64 v[50:51], 1, v[44:45]
	v_or_b32_e32 v6, v6, v148
	s_ashr_i32 s37, s36, 31
	v_lshl_add_u64 v[6:7], v[6:7], 0, v[50:51]
	s_lshl_b64 s[36:37], s[36:37], 15
	v_lshl_add_u64 v[54:55], s[82:83], 0, v[6:7]
	v_lshl_add_u64 v[6:7], s[36:37], 0, v[8:9]
	v_lshl_add_u64 v[10:11], v[10:11], 0, v[50:51]
	v_lshl_or_b32 v6, v4, 4, v6
	v_lshlrev_b32_e32 v48, 2, v4
	v_cmp_eq_u32_e64 s[6:7], 1, v4
	v_cmp_eq_u32_e64 s[8:9], 2, v4
	v_cmp_eq_u32_e64 s[10:11], 3, v4
	v_cmp_eq_u32_e64 s[12:13], 4, v4
	v_cmp_eq_u32_e64 s[14:15], 5, v4
	v_cmp_eq_u32_e64 s[16:17], 6, v4
	v_cmp_eq_u32_e64 s[18:19], 7, v4
	v_cmp_lt_u32_e64 s[30:31], 1, v4
	v_cmp_lt_u32_e64 s[28:29], 2, v4
	v_cmp_lt_u32_e64 s[26:27], 3, v4
	v_cmp_lt_u32_e64 s[24:25], 4, v4
	v_cmp_lt_u32_e64 s[20:21], 5, v4
	v_lshl_add_u64 v[52:53], s[78:79], 0, v[10:11]
	v_lshl_add_u64 v[56:57], s[62:63], 0, v[6:7]
	v_lshl_add_u64 v[58:59], s[84:85], 0, v[6:7]
	s_mov_b64 s[92:93], 0
	s_mov_b32 s33, 0xa100
	v_add_u32_e32 v73, v79, v5
	v_readlane_b32 s57, v254, 44
	v_readlane_b32 s58, v254, 45
	v_readlane_b32 s59, v254, 46
	v_readlane_b32 s60, v254, 47
	v_readlane_b32 s61, v254, 48
	v_readlane_b32 s64, v254, 51
	v_readlane_b32 s65, v254, 52
	v_readlane_b32 s66, v254, 53
	v_readlane_b32 s67, v254, 54
	v_readlane_b32 s68, v254, 55
	v_readlane_b32 s69, v254, 56
	v_readlane_b32 s70, v254, 57
	v_readlane_b32 s71, v254, 58
	global_load_dword v119, v149, s[88:89]
	global_load_dword v120, v149, s[86:87]
	global_load_ushort v118, v[52:53], off
	s_waitcnt vmcnt(0)
	s_branch .LBB0_678

; __device__ __forceinline__ void sample_ssd(const Params& p, unsigned char* smem, int job) {
;     ...
;     for (int hh = 0; hh < 16; ++hh) {
;         const int h = g * 16 + hh;
;         const float A_h = -__expf(p.in[14][h]), D_h = p.in[15][h];
;         float dtv[8], cum[8];
;         { float run = 0.f;
; #pragma unroll
;           for (int t = 0; t < 8; ++t) { dtv[t] = dts[hh * 8 + t]; run += dtv[t] * A_h; cum[t] = run; } }
;         const size_t soff = ((size_t)(b * 32 + h) * 64 + pp) * 128 + nq * 4;
;         f32x4 s0[4];
; #pragma unroll
;         for (int i = 0; i < 4; ++i) s0[i] = snext[i];
;         if (hh + 1 < 16) {
; #pragma unroll
;             for (int i = 0; i < 4; ++i) snext[i] = __builtin_nontemporal_load((const f32x4*)(p.in[3] + soff + 64 * 128 + 32 * i));
;         }
;         float cs[8];
; #pragma unroll
;         for (int t = 0; t < 8; ++t) {
;             float sum = 0.f;
; #pragma unroll
;             for (int i = 0; i < 4; ++i) { const f32x4 c4 = *(const f32x4*)(Cc + t * 128 + nq * 4 + 32 * i); sum += c4[0] * s0[i][0] + c4[1] * s0[i][1] + c4[2] * s0[i][2] + c4[3] * s0[i][3]; }
;             sum += __shfl_xor(sum, 1); sum += __shfl_xor(sum, 2); sum += __shfl_xor(sum, 4);
.LBB0_678:
	v_mov_b32_e32 v4, v119
	v_mov_b32_e32 v60, v120
	v_mov_b32_e32 v121, v118
	global_load_dword v119, v149, s[88:89] offset:4
	global_load_dword v120, v149, s[86:87] offset:4
	global_load_ushort v118, v[52:53], off offset:128
	s_add_i32 s36, s33, 0
	v_mov_b32_e32 v5, s36
	ds_read_b128 v[40:43], v5
	ds_read_b128 v[36:39], v5 offset:16
	s_mov_b32 s36, 0x8000
	v_add_u32_e32 v94, 0, v85
	v_mov_b32_e32 v111, 0
	v_mov_b32_e32 v112, 0
	v_mul_f32_e32 v4, 0x3fb8aa3b, v4
	v_exp_f32_e32 v4, v4
	s_waitcnt lgkmcnt(1)
	v_fma_f32 v93, -v4, v40, 0
	v_fma_f32 v92, -v4, v41, v93
	v_fma_f32 v91, -v4, v42, v92
	v_fma_f32 v90, -v4, v43, v91
	s_waitcnt lgkmcnt(0)
	v_fma_f32 v89, -v4, v36, v90
	v_fma_f32 v88, -v4, v37, v89
	v_fma_f32 v86, -v4, v38, v88
	v_fma_f32 v87, -v4, v39, v86
	v_lshl_add_u64 v[4:5], v[56:57], 0, s[92:93]
	v_add_co_u32_e64 v4, s[36:37], s36, v4
	s_nop 1
	v_addc_co_u32_e64 v5, s[36:37], 0, v5, s[36:37]
	global_load_dwordx4 v[16:19], v[4:5], off nt
	global_load_dwordx4 v[12:15], v[4:5], off offset:128 nt
	global_load_dwordx4 v[8:11], v[4:5], off offset:256 nt
	s_nop 0
	global_load_dwordx4 v[4:7], v[4:5], off offset:384 nt
	ds_read_b128 v[62:65], v83 offset:4096
	s_waitcnt lgkmcnt(0)
	v_mul_f32_e32 v61, v33, v63
	v_fmac_f32_e32 v61, v32, v62
	v_fmac_f32_e32 v61, v34, v64
	v_fmac_f32_e32 v61, v35, v65
	ds_read_b128 v[62:65], v83 offset:4224
	v_add_f32_e32 v61, 0, v61
	s_waitcnt lgkmcnt(0)
	v_mul_f32_e32 v63, v29, v63
	v_fmac_f32_e32 v63, v28, v62
	v_fmac_f32_e32 v63, v30, v64
	v_fmac_f32_e32 v63, v31, v65
	v_add_f32_e32 v61, v61, v63
	ds_read_b128 v[62:65], v83 offset:4352
	s_waitcnt lgkmcnt(0)
	v_mul_f32_e32 v63, v25, v63
	v_fmac_f32_e32 v63, v24, v62
	v_fmac_f32_e32 v63, v26, v64
	v_fmac_f32_e32 v63, v27, v65
	v_add_f32_e32 v61, v61, v63
	ds_read_b128 v[62:65], v83 offset:4480
	s_waitcnt lgkmcnt(0)
	v_mul_f32_e32 v63, v21, v63
	v_fmac_f32_e32 v63, v20, v62
	v_fmac_f32_e32 v63, v22, v64
	v_fmac_f32_e32 v63, v23, v65
	v_add_f32_e32 v61, v61, v63
	ds_bpermute_b32 v62, v82, v61
	s_waitcnt lgkmcnt(0)
	v_add_f32_e32 v61, v61, v62
	ds_bpermute_b32 v62, v81, v61
	s_waitcnt lgkmcnt(0)
	v_add_f32_e32 v61, v61, v62
	ds_read_b128 v[62:65], v83 offset:4608
	ds_bpermute_b32 v67, v80, v61
	s_waitcnt lgkmcnt(1)
	v_mul_f32_e32 v63, v33, v63
	v_fmac_f32_e32 v63, v32, v62
	v_fmac_f32_e32 v63, v34, v64
	v_fmac_f32_e32 v63, v35, v65
	v_add_f32_e32 v66, 0, v63
	ds_read_b128 v[62:65], v83 offset:4736
	s_waitcnt lgkmcnt(0)
	v_mul_f32_e32 v63, v29, v63
	v_fmac_f32_e32 v63, v28, v62
	v_fmac_f32_e32 v63, v30, v64
	v_fmac_f32_e32 v63, v31, v65
	v_add_f32_e32 v66, v66, v63
	ds_read_b128 v[62:65], v83 offset:4864
	s_waitcnt lgkmcnt(0)
	v_mul_f32_e32 v63, v25, v63
	v_fmac_f32_e32 v63, v24, v62
	v_fmac_f32_e32 v63, v26, v64
	v_fmac_f32_e32 v63, v27, v65
	v_add_f32_e32 v66, v66, v63
	ds_read_b128 v[62:65], v83 offset:4992
	s_waitcnt lgkmcnt(0)
	v_mul_f32_e32 v63, v21, v63
	v_fmac_f32_e32 v63, v20, v62
	v_fmac_f32_e32 v63, v22, v64
	v_fmac_f32_e32 v63, v23, v65
	v_add_f32_e32 v62, v66, v63
	ds_bpermute_b32 v63, v82, v62
	s_waitcnt lgkmcnt(0)
	v_add_f32_e32 v62, v62, v63
	ds_bpermute_b32 v63, v81, v62
	s_waitcnt lgkmcnt(0)
	v_add_f32_e32 v72, v62, v63
	ds_read_b128 v[62:65], v83 offset:5120
	ds_bpermute_b32 v95, v80, v72
	s_waitcnt lgkmcnt(1)
	v_mul_f32_e32 v63, v33, v63
	v_fmac_f32_e32 v63, v32, v62
	v_fmac_f32_e32 v63, v34, v64
	v_fmac_f32_e32 v63, v35, v65
	v_add_f32_e32 v66, 0, v63
	ds_read_b128 v[62:65], v83 offset:5248
	s_waitcnt lgkmcnt(0)
	v_mul_f32_e32 v63, v29, v63
	v_fmac_f32_e32 v63, v28, v62
	v_fmac_f32_e32 v63, v30, v64
	v_fmac_f32_e32 v63, v31, v65
	v_add_f32_e32 v66, v66, v63
	ds_read_b128 v[62:65], v83 offset:5376
	s_waitcnt lgkmcnt(0)
	v_mul_f32_e32 v63, v25, v63
	v_fmac_f32_e32 v63, v24, v62
	v_fmac_f32_e32 v63, v26, v64
	v_fmac_f32_e32 v63, v27, v65
	v_add_f32_e32 v66, v66, v63
	ds_read_b128 v[62:65], v83 offset:5504
	s_waitcnt lgkmcnt(0)
	v_mul_f32_e32 v63, v21, v63
	v_fmac_f32_e32 v63, v20, v62
	v_fmac_f32_e32 v63, v22, v64
	v_fmac_f32_e32 v63, v23, v65
	v_add_f32_e32 v62, v66, v63
	ds_bpermute_b32 v63, v82, v62
	s_waitcnt lgkmcnt(0)
	v_add_f32_e32 v62, v62, v63
	ds_bpermute_b32 v63, v81, v62
	s_waitcnt lgkmcnt(0)
	v_add_f32_e32 v96, v62, v63
	ds_read_b128 v[62:65], v83 offset:5632
	ds_bpermute_b32 v97, v80, v96
	s_waitcnt lgkmcnt(1)
	v_mul_f32_e32 v63, v33, v63
	v_fmac_f32_e32 v63, v32, v62
	v_fmac_f32_e32 v63, v34, v64
	v_fmac_f32_e32 v63, v35, v65
	v_add_f32_e32 v66, 0, v63
	ds_read_b128 v[62:65], v83 offset:5760
	s_waitcnt lgkmcnt(0)
	v_mul_f32_e32 v63, v29, v63
	v_fmac_f32_e32 v63, v28, v62
	v_fmac_f32_e32 v63, v30, v64
	v_fmac_f32_e32 v63, v31, v65
	v_add_f32_e32 v66, v66, v63
	ds_read_b128 v[62:65], v83 offset:5888
	s_waitcnt lgkmcnt(0)
	v_mul_f32_e32 v63, v25, v63
	v_fmac_f32_e32 v63, v24, v62
	v_fmac_f32_e32 v63, v26, v64
	v_fmac_f32_e32 v63, v27, v65
	v_add_f32_e32 v66, v66, v63
	ds_read_b128 v[62:65], v83 offset:6016
	s_waitcnt lgkmcnt(0)
	v_mul_f32_e32 v63, v21, v63
	v_fmac_f32_e32 v63, v20, v62
	v_fmac_f32_e32 v63, v22, v64
	v_fmac_f32_e32 v63, v23, v65
	v_add_f32_e32 v62, v66, v63
	ds_bpermute_b32 v63, v82, v62
	s_waitcnt lgkmcnt(0)
; __device__ __forceinline__ void sample_ssd(const Params& p, unsigned char* smem, int job) {
;     ...
;         for (int t = 0; t < 8; ++t) {
;             float sum = 0.f;
; #pragma unroll
;             for (int i = 0; i < 4; ++i) { const f32x4 c4 = *(const f32x4*)(Cc + t * 128 + nq * 4 + 32 * i); sum += c4[0] * s0[i][0] + c4[1] * s0[i][1] + c4[2] * s0[i][2] + c4[3] * s0[i][3]; }
;             sum += __shfl_xor(sum, 1); sum += __shfl_xor(sum, 2); sum += __shfl_xor(sum, 4);
;             cs[t] = sum;
;         }
;         float ycs = 0.f, ct = 0.f;
; #pragma unroll
;         for (int t = 0; t < 8; ++t) { ycs = (nq == t) ? cs[t] : ycs; ct = (nq == t) ? cum[t] : ct; }
;         float y = __expf(ct) * ycs, xt = 0.f;
; #pragma unroll
;         for (int s = 0; s < 8; ++s) {
;             const float xs = xall[s * 1024 + hh * 64 + pp];
;             const float term = (s <= nq) ? G[nq * 8 + s] * __expf(ct - cum[s]) * dtv[s] * xs : 0.f;
;             y += term; xt = (s == nq) ? xs : xt;
	v_add_f32_e32 v62, v62, v63
	ds_bpermute_b32 v63, v81, v62
	s_waitcnt lgkmcnt(0)
	v_add_f32_e32 v98, v62, v63
	ds_read_b128 v[62:65], v83 offset:6144
	ds_bpermute_b32 v99, v80, v98
	s_waitcnt lgkmcnt(1)
	v_mul_f32_e32 v63, v33, v63
	v_fmac_f32_e32 v63, v32, v62
	v_fmac_f32_e32 v63, v34, v64
	v_fmac_f32_e32 v63, v35, v65
	v_add_f32_e32 v66, 0, v63
	ds_read_b128 v[62:65], v83 offset:6272
	s_waitcnt lgkmcnt(0)
	v_mul_f32_e32 v63, v29, v63
	v_fmac_f32_e32 v63, v28, v62
	v_fmac_f32_e32 v63, v30, v64
	v_fmac_f32_e32 v63, v31, v65
	v_add_f32_e32 v66, v66, v63
	ds_read_b128 v[62:65], v83 offset:6400
	s_waitcnt lgkmcnt(0)
	v_mul_f32_e32 v63, v25, v63
	v_fmac_f32_e32 v63, v24, v62
	v_fmac_f32_e32 v63, v26, v64
	v_fmac_f32_e32 v63, v27, v65
	v_add_f32_e32 v66, v66, v63
	ds_read_b128 v[62:65], v83 offset:6528
	s_waitcnt lgkmcnt(0)
	v_mul_f32_e32 v63, v21, v63
	v_fmac_f32_e32 v63, v20, v62
	v_fmac_f32_e32 v63, v22, v64
	v_fmac_f32_e32 v63, v23, v65
	v_add_f32_e32 v62, v66, v63
	ds_bpermute_b32 v63, v82, v62
	s_waitcnt lgkmcnt(0)
	v_add_f32_e32 v62, v62, v63
	ds_bpermute_b32 v63, v81, v62
	s_waitcnt lgkmcnt(0)
	v_add_f32_e32 v100, v62, v63
	ds_read_b128 v[62:65], v83 offset:6656
	ds_bpermute_b32 v101, v80, v100
	s_waitcnt lgkmcnt(1)
	v_mul_f32_e32 v63, v33, v63
	v_fmac_f32_e32 v63, v32, v62
	v_fmac_f32_e32 v63, v34, v64
	v_fmac_f32_e32 v63, v35, v65
	v_add_f32_e32 v66, 0, v63
	ds_read_b128 v[62:65], v83 offset:6784
	s_waitcnt lgkmcnt(0)
	v_mul_f32_e32 v63, v29, v63
	v_fmac_f32_e32 v63, v28, v62
	v_fmac_f32_e32 v63, v30, v64
	v_fmac_f32_e32 v63, v31, v65
	v_add_f32_e32 v66, v66, v63
	ds_read_b128 v[62:65], v83 offset:6912
	s_waitcnt lgkmcnt(0)
	v_mul_f32_e32 v63, v25, v63
	v_fmac_f32_e32 v63, v24, v62
	v_fmac_f32_e32 v63, v26, v64
	v_fmac_f32_e32 v63, v27, v65
	v_add_f32_e32 v66, v66, v63
	ds_read_b128 v[62:65], v83 offset:7040
	s_waitcnt lgkmcnt(0)
	v_mul_f32_e32 v63, v21, v63
	v_fmac_f32_e32 v63, v20, v62
	v_fmac_f32_e32 v63, v22, v64
	v_fmac_f32_e32 v63, v23, v65
	v_add_f32_e32 v62, v66, v63
	ds_bpermute_b32 v63, v82, v62
	s_waitcnt lgkmcnt(0)
	v_add_f32_e32 v62, v62, v63
	ds_bpermute_b32 v63, v81, v62
	s_waitcnt lgkmcnt(0)
	v_add_f32_e32 v102, v62, v63
	ds_read_b128 v[62:65], v83 offset:7168
	ds_bpermute_b32 v103, v80, v102
	s_waitcnt lgkmcnt(1)
	v_mul_f32_e32 v63, v33, v63
	v_fmac_f32_e32 v63, v32, v62
	v_fmac_f32_e32 v63, v34, v64
	v_fmac_f32_e32 v63, v35, v65
	v_add_f32_e32 v66, 0, v63
	ds_read_b128 v[62:65], v83 offset:7296
	s_waitcnt lgkmcnt(0)
	v_mul_f32_e32 v63, v29, v63
	v_fmac_f32_e32 v63, v28, v62
	v_fmac_f32_e32 v63, v30, v64
	v_fmac_f32_e32 v63, v31, v65
	v_add_f32_e32 v66, v66, v63
	ds_read_b128 v[62:65], v83 offset:7424
	s_waitcnt lgkmcnt(0)
	v_mul_f32_e32 v63, v25, v63
	v_fmac_f32_e32 v63, v24, v62
	v_fmac_f32_e32 v63, v26, v64
	v_fmac_f32_e32 v63, v27, v65
	v_add_f32_e32 v66, v66, v63
	ds_read_b128 v[62:65], v83 offset:7552
	s_waitcnt lgkmcnt(0)
	v_mul_f32_e32 v63, v21, v63
	v_fmac_f32_e32 v63, v20, v62
	v_fmac_f32_e32 v63, v22, v64
	v_fmac_f32_e32 v63, v23, v65
	v_add_f32_e32 v62, v66, v63
	ds_bpermute_b32 v63, v82, v62
	s_waitcnt lgkmcnt(0)
	v_add_f32_e32 v62, v62, v63
	ds_bpermute_b32 v63, v81, v62
	s_waitcnt lgkmcnt(0)
	v_add_f32_e32 v104, v62, v63
	ds_read_b128 v[62:65], v83 offset:7680
	ds_bpermute_b32 v105, v80, v104
	s_waitcnt lgkmcnt(1)
	v_mul_f32_e32 v63, v33, v63
	v_fmac_f32_e32 v63, v32, v62
	v_fmac_f32_e32 v63, v34, v64
	v_fmac_f32_e32 v63, v35, v65
	v_add_f32_e32 v66, 0, v63
	ds_read_b128 v[62:65], v83 offset:7808
	s_waitcnt lgkmcnt(0)
	v_mul_f32_e32 v63, v29, v63
	v_fmac_f32_e32 v63, v28, v62
	v_fmac_f32_e32 v63, v30, v64
	v_fmac_f32_e32 v63, v31, v65
	v_add_f32_e32 v66, v66, v63
	ds_read_b128 v[62:65], v83 offset:7936
	s_waitcnt lgkmcnt(0)
	v_mul_f32_e32 v63, v25, v63
	v_fmac_f32_e32 v63, v24, v62
	v_fmac_f32_e32 v63, v26, v64
	v_fmac_f32_e32 v63, v27, v65
	v_add_f32_e32 v66, v66, v63
	ds_read_b128 v[62:65], v83 offset:8064
	s_waitcnt lgkmcnt(0)
	v_mul_f32_e32 v63, v21, v63
	v_fmac_f32_e32 v63, v20, v62
	v_fmac_f32_e32 v63, v22, v64
	v_fmac_f32_e32 v63, v23, v65
	v_add_f32_e32 v62, v66, v63
	ds_bpermute_b32 v63, v82, v62
	s_waitcnt lgkmcnt(0)
	v_add_f32_e32 v62, v62, v63
	ds_bpermute_b32 v63, v81, v62
	s_waitcnt lgkmcnt(0)
	v_add_f32_e32 v107, v62, v63
	v_cndmask_b32_e64 v62, 0, v93, s[4:5]
	v_cndmask_b32_e64 v62, v62, v92, s[6:7]
	v_cndmask_b32_e64 v62, v62, v91, s[8:9]
	v_cndmask_b32_e64 v62, v62, v90, s[10:11]
	v_cndmask_b32_e64 v62, v62, v89, s[12:13]
	v_cndmask_b32_e64 v62, v62, v88, s[14:15]
	v_cndmask_b32_e64 v62, v62, v86, s[16:17]
	ds_bpermute_b32 v108, v80, v107
	v_cndmask_b32_e64 v106, v62, v87, s[18:19]
	ds_read2st64_b32 v[62:63], v94 offset1:16
	ds_read_b32 v109, v79 offset:40960
	s_and_saveexec_b64 s[36:37], s[22:23]
	s_cbranch_execz .LBB0_680
	v_sub_f32_e32 v64, v106, v92
	v_mul_f32_e32 v64, 0x3fb8aa3b, v64
	ds_read_b32 v65, v79 offset:40964
	v_exp_f32_e32 v64, v64
	s_waitcnt lgkmcnt(0)
	v_mul_f32_e32 v64, v64, v65
	v_mul_f32_e32 v64, v41, v64
	v_mul_f32_e32 v112, v63, v64

; __device__ __forceinline__ unsigned pack2(float lo, float hi) { unsigned r; asm("v_cvt_pk_bf16_f32 %0, %1, %2" : "=v"(r) : "v"(lo), "v"(hi)); return r; }
; __device__ __forceinline__ float bf2f(bf16_t h) { return __uint_as_float((unsigned)h << 16); }
; __device__ __forceinline__ float silu_f(float x) { return x * sigm_f(x); }
; __device__ __forceinline__ void sample_ssd(const Params& p, unsigned char* smem, int job) {
;     ...
;             y += term; xt = (s == nq) ? xs : xt;
;         }
;         y += D_h * xt;
;         const float z = bf2f(U[(size_t)(rowb + nq) * N1P + UC_Z + h * 64 + pp]);
;         y *= silu_f(z);
;         { const unsigned pk = pack2(y, 0.f); MIX[(size_t)(rowb + nq) * MIXW + h * 64 + pp] = (bf16_t)(pk & 0xffffu); }
;         float sq = y * y; sq += __shfl_xor(sq, 8); sq += __shfl_xor(sq, 16); sq += __shfl_xor(sq, 32);
;         if (lane < 8) ssqp[(hh * 8 + wid) * 8 + lane] = sq;
.LBB0_692:
	s_or_b64 exec, exec, s[36:37]
	v_add_f32_e32 v61, v61, v67
	v_add_f32_e32 v72, v72, v95
	v_cndmask_b32_e64 v61, 0, v61, s[4:5]
	v_add_f32_e32 v95, v96, v97
	v_cndmask_b32_e64 v61, v61, v72, s[6:7]
	v_add_f32_e32 v96, v98, v99
	v_cndmask_b32_e64 v61, v61, v95, s[8:9]
	v_add_f32_e32 v97, v100, v101
	v_cndmask_b32_e64 v61, v61, v96, s[10:11]
	v_mul_f32_e32 v67, 0x3fb8aa3b, v106
	v_add_f32_e32 v98, v102, v103
	v_cndmask_b32_e64 v61, v61, v97, s[12:13]
	v_exp_f32_e32 v67, v67
	v_add_f32_e32 v99, v104, v105
	v_cndmask_b32_e64 v61, v61, v98, s[14:15]
	v_add_f32_e32 v100, v107, v108
	v_cndmask_b32_e64 v61, v61, v99, s[16:17]
	v_cndmask_b32_e64 v61, v61, v100, s[18:19]
	v_mul_f32_e32 v61, v67, v61
	v_sub_f32_e32 v67, v106, v93
	v_mul_f32_e32 v67, 0x3fb8aa3b, v67
	v_exp_f32_e32 v67, v67
	s_nop 0
	v_mul_f32_e32 v67, v67, v109
	v_mul_f32_e32 v67, v40, v67
	v_fmac_f32_e32 v61, v62, v67
	v_add_f32_e32 v61, v61, v112
	v_add_f32_e32 v61, v61, v113
	v_add_f32_e32 v61, v61, v111
	v_add_f32_e32 v61, v61, v115
	v_add_f32_e32 v61, v61, v114
	v_add_f32_e32 v61, v61, v117
	v_add_f32_e32 v72, v61, v116
	v_mov_b32_e32 v61, v121
	v_lshlrev_b32_e32 v95, 16, v61
	v_max_f32_e64 v61, -v95, -v95
	v_min_f32_e32 v61, 0x42a00000, v61
	v_mul_f32_e32 v61, 0x3fb8aa3b, v61
	v_exp_f32_e32 v61, v61
	s_nop 0
	v_add_f32_e32 v67, 1.0, v61
	v_rcp_f32_e32 v61, v67
	s_nop 0
	v_fma_f32 v67, -v67, v61, 2.0
	v_pk_fma_f32 v[96:97], v[60:61], v[66:67], v[72:73]
	v_mul_f32_e32 v60, v61, v67
	v_mul_f32_e32 v60, v60, v95
	v_mul_f32_e32 v60, v96, v60
	v_cvt_pk_bf16_f32 v61, v60, v149
	global_store_short v[54:55], v61, off
	v_mul_f32_e32 v61, v60, v60
	ds_bpermute_b32 v61, v77, v61
	s_waitcnt lgkmcnt(0)
	v_fmac_f32_e32 v61, v60, v60
	ds_bpermute_b32 v60, v78, v61
	s_waitcnt lgkmcnt(0)
	v_add_f32_e32 v60, v61, v60
	ds_bpermute_b32 v61, v76, v60
	s_and_saveexec_b64 s[36:37], s[0:1]
	s_cbranch_execz .LBB0_677
	v_add_u32_e32 v62, 0, v84
	s_waitcnt lgkmcnt(0)
	v_add_f32_e32 v60, v60, v61
	ds_write_b32 v62, v60
	ds_read2st64_b32 v[62:63], v94 offset1:16
	ds_read2st64_b32 v[64:65], v94 offset0:32 offset1:48
	ds_read2st64_b32 v[68:69], v94 offset0:64 offset1:80
	ds_read2st64_b32 v[70:71], v94 offset0:96 offset1:112
	s_branch .LBB0_677
